# prologue phase: odd waves run the x_prompt norm rows before the weight-conversion items so the bandwidth-bound and latency-bound parts overlap
# baseline (speedup 1.0000x reference)
.LBB0_1065:
	s_and_b64 vcc, exec, s[0:1]
	s_cbranch_vccz .LBB0_1137
	s_mov_b32 s101, 0
	v_readlane_b32 s0, v250, 25
	s_nop 3
	s_bitcmp1_b32 s0, 6
	s_cbranch_scc0 .Lp0_main
	s_mov_b32 s101, 1
	v_mbcnt_lo_u32_b32 v66, -1, 0
	v_mbcnt_hi_u32_b32 v66, -1, v66
	s_branch .LBB0_1133
.Lp0_main:
	s_mov_b32 s0, -1
	s_nop 0
	v_mbcnt_lo_u32_b32 v0, s0, 0
	v_mbcnt_hi_u32_b32 v0, s0, v0
	v_readlane_b32 s0, v250, 25
	s_nop 1
	v_add_u32_e32 v65, s0, v0
	v_readlane_b32 s0, v250, 49
	v_readlane_b32 s1, v250, 50
	s_andn2_b64 vcc, exec, s[0:1]
	s_cbranch_vccnz .LBB0_1074
	v_readlane_b32 s0, v250, 51
	v_readlane_b32 s1, v250, 52
	s_andn2_b64 vcc, exec, s[0:1]
	s_cbranch_vccnz .LBB0_1075
	v_readlane_b32 s0, v250, 53
	v_readlane_b32 s1, v250, 54
	s_andn2_b64 vcc, exec, s[0:1]
	s_cbranch_vccnz .LBB0_1076
	v_readlane_b32 s0, v250, 55
	v_readlane_b32 s1, v250, 56
	s_andn2_b64 vcc, exec, s[0:1]
	s_cbranch_vccnz .LBB0_1077
	v_readlane_b32 s0, v250, 57
	v_readlane_b32 s1, v250, 58
	s_andn2_b64 vcc, exec, s[0:1]
	s_cbranch_vccnz .LBB0_1078
	v_readlane_b32 s0, v250, 59
	v_readlane_b32 s1, v250, 60
	s_andn2_b64 vcc, exec, s[0:1]
	s_cbranch_vccnz .LBB0_1079
	v_readlane_b32 s0, v250, 61
	v_readlane_b32 s1, v250, 62
	s_andn2_b64 vcc, exec, s[0:1]
	s_cbranch_vccnz .LBB0_1080
	v_readlane_b32 s0, v253, 17
	v_readlane_b32 s8, v253, 13
	v_readlane_b32 s4, v253, 11
	v_readlane_b32 s3, v253, 21
	v_readlane_b32 s10, v253, 20
	v_readlane_b32 s2, v253, 19
	v_readlane_b32 s1, v253, 18
	v_readlane_b32 s9, v253, 14
	v_readlane_b32 s5, v253, 12
	s_branch .LBB0_1081

.LBB0_1133:
	s_cmp_eq_u32 s101, 2
	s_cbranch_scc1 .LBB0_1136
	v_readlane_b32 s0, v250, 38
	v_readlane_b32 s1, v250, 39
	s_andn2_b64 vcc, exec, s[0:1]
	s_cbranch_vccnz .LBB0_1136
	v_and_b32_e32 v0, 64, v178
	v_add_u32_e32 v0, 64, v0
	v_xor_b32_e32 v1, 1, v178
	v_cmp_lt_i32_e32 vcc, v1, v0
	v_readlane_b32 s0, v254, 18
	v_readlane_b32 s1, v254, 19
	v_cndmask_b32_e32 v1, v178, v1, vcc
	v_lshlrev_b32_e32 v4, 2, v1
	v_xor_b32_e32 v1, 2, v178
	v_cmp_lt_i32_e32 vcc, v1, v0
	v_lshlrev_b32_e32 v2, 4, v66
	v_mov_b32_e32 v3, v64
	v_cndmask_b32_e32 v1, v178, v1, vcc
	v_lshlrev_b32_e32 v5, 2, v1
	v_xor_b32_e32 v1, 4, v178
	v_cmp_lt_i32_e32 vcc, v1, v0
	v_readlane_b32 s2, v254, 20
	v_readlane_b32 s3, v254, 21
	v_cndmask_b32_e32 v1, v178, v1, vcc
	v_lshlrev_b32_e32 v6, 2, v1
	v_xor_b32_e32 v1, 8, v178
	v_cmp_lt_i32_e32 vcc, v1, v0
	s_nop 1
	v_cndmask_b32_e32 v1, v178, v1, vcc
	v_lshlrev_b32_e32 v7, 2, v1
	v_xor_b32_e32 v1, 16, v178
	v_cmp_lt_i32_e32 vcc, v1, v0
	s_nop 1
	v_cndmask_b32_e32 v1, v178, v1, vcc
	v_lshlrev_b32_e32 v8, 2, v1
	v_xor_b32_e32 v1, 32, v178
	v_cmp_lt_i32_e32 vcc, v1, v0
	s_nop 1
	v_cndmask_b32_e32 v0, v178, v1, vcc
	v_lshlrev_b32_e32 v9, 2, v0
	v_lshlrev_b32_e32 v0, 3, v66
	v_mov_b32_e32 v1, v64
	v_lshl_add_u64 v[0:1], s[0:1], 0, v[0:1]
	v_readlane_b32 s0, v254, 52
	v_readlane_b32 s1, v254, 53
	s_nop 1
	v_lshl_add_u64 v[2:3], s[0:1], 0, v[2:3]
	v_readlane_b32 s0, v254, 55
	v_readlane_b32 s1, v254, 56

.LBB0_1136:
	s_cmp_eq_u32 s101, 1
	s_cbranch_scc0 .Lp0_end
	s_mov_b32 s101, 2
	s_branch .Lp0_main
